# C-attention loop: next-step K-fragment LDS reads moved from the first PV half (LDS-saturated by V transpose reads) to the second PV half; lgkmcnt waits re-derived
# speedup vs baseline: 1.0068x; 1.0067x over previous
.LBB0_442:
	s_mov_b32 s30, s62
	v_mov_b64_e32 v[218:219], v[96:97]
	s_mov_b32 s63, s33
	s_mov_b32 s3, s61
	v_lshl_add_u32 v206, s36, 14, v241
	ds_read_b64_tr_b16 v[196:197], v206 offset:24576
	ds_read_b64_tr_b16 v[198:199], v206 offset:25088
	v_add_f32_e32 v96, v80, v81
	v_add_f32_e32 v96, v82, v96
	v_add_f32_e32 v96, v83, v96
	v_add_f32_e32 v96, v84, v96
	v_add_f32_e32 v96, v85, v96
	v_cvt_pk_bf16_f32 v140, v80, v81
	v_cvt_pk_bf16_f32 v141, v82, v83
	v_mfma_f32_32x32x16_bf16 v[112:127], v[188:191], v[156:159], 0
	ds_read_b64_tr_b16 v[80:81], v206 offset:28672
	ds_read_b64_tr_b16 v[82:83], v206 offset:29184
	v_add_f32_e32 v96, v86, v96
	v_add_f32_e32 v96, v87, v96
	v_add_f32_e32 v96, v88, v96
	v_add_f32_e32 v128, v89, v96
	v_mfma_f32_32x32x16_bf16 v[96:111], v[180:183], v[156:159], 0
	v_cvt_pk_bf16_f32 v142, v84, v85
	v_cvt_pk_bf16_f32 v143, v86, v87
	ds_read_b64_tr_b16 v[84:85], v206 offset:25600
	ds_read_b64_tr_b16 v[86:87], v206 offset:26112
	v_add_f32_e32 v128, v90, v128
	v_add_f32_e32 v128, v91, v128
	v_add_f32_e32 v128, v92, v128
	v_add_f32_e32 v128, v93, v128
	v_cvt_pk_bf16_f32 v136, v88, v89
	v_cvt_pk_bf16_f32 v137, v90, v91
	v_mfma_f32_32x32x16_bf16 v[112:127], v[184:187], v[152:155], v[112:127]
	ds_read_b64_tr_b16 v[88:89], v206 offset:29696
	ds_read_b64_tr_b16 v[90:91], v206 offset:30208
	v_mfma_f32_32x32x16_bf16 v[96:111], v[176:179], v[152:155], v[96:111]
	v_add_f32_e32 v128, v94, v128
	v_add_f32_e32 v128, v95, v128
	v_add_f32_e32 v128, v64, v128
	v_add_f32_e32 v128, v65, v128
	v_cvt_pk_bf16_f32 v138, v92, v93
	v_cvt_pk_bf16_f32 v139, v94, v95
	ds_read_b64_tr_b16 v[92:93], v206 offset:26624
	ds_read_b64_tr_b16 v[94:95], v206 offset:27136
	v_add_f32_e32 v128, v66, v128
	v_add_f32_e32 v128, v67, v128
	v_add_f32_e32 v128, v68, v128
	v_add_f32_e32 v128, v69, v128
	v_cvt_pk_bf16_f32 v132, v64, v65
	v_cvt_pk_bf16_f32 v133, v66, v67
	v_mfma_f32_32x32x16_bf16 v[112:127], v[172:175], v[148:151], v[112:127]
	ds_read_b64_tr_b16 v[200:201], v206 offset:30720
	ds_read_b64_tr_b16 v[202:203], v206 offset:31232
	v_mfma_f32_32x32x16_bf16 v[96:111], v[168:171], v[148:151], v[96:111]
	v_add_f32_e32 v64, v70, v128
	v_add_f32_e32 v64, v71, v64
	v_add_f32_e32 v64, v72, v64
	v_add_f32_e32 v64, v73, v64
	v_cvt_pk_bf16_f32 v134, v68, v69
	v_cvt_pk_bf16_f32 v135, v70, v71
	ds_read_b64_tr_b16 v[242:243], v206 offset:27648
	ds_read_b64_tr_b16 v[244:245], v206 offset:28160
	v_add_f32_e32 v64, v74, v64
	v_add_f32_e32 v64, v75, v64
	v_add_f32_e32 v64, v76, v64
	v_add_f32_e32 v64, v77, v64
	v_cvt_pk_bf16_f32 v128, v72, v73
	v_cvt_pk_bf16_f32 v129, v74, v75
	v_mfma_f32_32x32x16_bf16 v[112:127], v[164:167], v[144:147], v[112:127]
	ds_read_b64_tr_b16 v[72:73], v206 offset:31744
	ds_read_b64_tr_b16 v[74:75], v206 offset:32256
	v_mfma_f32_32x32x16_bf16 v[96:111], v[160:163], v[144:147], v[96:111]
	v_add_f32_e32 v64, v78, v64
	v_add_f32_e32 v64, v79, v64
	v_add_f32_e32 v64, 0, v64
	v_cvt_pk_bf16_f32 v130, v76, v77
	v_cvt_pk_bf16_f32 v131, v78, v79
	v_lshl_add_u64 v[186:187], v[194:195], 0, s[4:5]
	s_mov_b64 s[34:35], 0xb622a00
	s_lshl_b32 s31, s61, 13
	v_add_f32_e32 v188, v204, v64
	v_lshl_add_u64 v[64:65], v[186:187], 0, s[34:35]
	s_add_i32 s31, s31, s58
	s_mov_b32 s33, m0
	s_mov_b32 m0, s31
	s_nop 0
	global_load_lds_dwordx4 v[64:65], off
	s_mov_b32 m0, s33
	v_lshl_add_u64 v[184:185], v[192:193], 0, s[4:5]
	s_mov_b64 s[34:35], 0xb412e00
	s_lshl_b32 s64, s62, 14
	v_lshl_add_u64 v[64:65], v[184:185], 0, s[34:35]
	s_add_i32 s31, s64, s59
	s_mov_b32 s33, m0
	s_mov_b32 m0, s31
	s_nop 0
	global_load_lds_dwordx4 v[64:65], off
	s_mov_b32 m0, s33
	s_mov_b64 s[34:35], 0xb412e80
	v_lshl_add_u64 v[64:65], v[184:185], 0, s[34:35]
	s_addk_i32 s31, 0x2000
	s_mov_b32 s33, m0
	s_mov_b32 m0, s31
	s_nop 0
	global_load_lds_dwordx4 v[64:65], off
	s_mov_b32 m0, s33
	s_waitcnt lgkmcnt(14)
	v_mfma_f32_32x32x16_bf16 v[48:63], v[140:143], v[196:199], v[48:63]
	v_exp_f32_e32 v112, v112
	v_exp_f32_e32 v113, v113
	ds_read_b64_tr_b16 v[76:77], v206 offset:32768
	ds_read_b64_tr_b16 v[78:79], v206 offset:33280
	s_waitcnt lgkmcnt(14)
	v_mfma_f32_32x32x16_bf16 v[32:47], v[140:143], v[80:83], v[32:47]
	v_exp_f32_e32 v114, v114
	v_exp_f32_e32 v115, v115
	ds_read_b64_tr_b16 v[80:81], v206 offset:36864
	ds_read_b64_tr_b16 v[82:83], v206 offset:37376
	s_waitcnt lgkmcnt(14)
	v_mfma_f32_32x32x16_bf16 v[48:63], v[136:139], v[84:87], v[48:63]
	v_exp_f32_e32 v116, v116
	v_exp_f32_e32 v117, v117
	ds_read_b64_tr_b16 v[84:85], v206 offset:33792
	ds_read_b64_tr_b16 v[86:87], v206 offset:34304
	s_waitcnt lgkmcnt(14)
	v_mfma_f32_32x32x16_bf16 v[32:47], v[136:139], v[88:91], v[32:47]
	v_exp_f32_e32 v118, v118
	v_exp_f32_e32 v119, v119
	ds_read_b64_tr_b16 v[88:89], v206 offset:37888
	ds_read_b64_tr_b16 v[90:91], v206 offset:38400
	s_waitcnt lgkmcnt(14)
	v_mfma_f32_32x32x16_bf16 v[48:63], v[132:135], v[92:95], v[48:63]
	v_exp_f32_e32 v120, v120
	v_exp_f32_e32 v121, v121
	ds_read_b64_tr_b16 v[92:93], v206 offset:34816
	ds_read_b64_tr_b16 v[94:95], v206 offset:35328
	s_waitcnt lgkmcnt(14)
	v_mfma_f32_32x32x16_bf16 v[32:47], v[132:135], v[200:203], v[32:47]
	v_exp_f32_e32 v122, v122
	v_exp_f32_e32 v123, v123
	ds_read_b64_tr_b16 v[196:197], v206 offset:38912
	ds_read_b64_tr_b16 v[198:199], v206 offset:39424
	s_waitcnt lgkmcnt(14)
	v_mfma_f32_32x32x16_bf16 v[48:63], v[128:131], v[242:245], v[48:63]
	v_exp_f32_e32 v124, v124
	v_exp_f32_e32 v125, v125
	ds_read_b64_tr_b16 v[200:201], v206 offset:35840
	ds_read_b64_tr_b16 v[202:203], v206 offset:36352
	s_waitcnt lgkmcnt(14)
	v_mfma_f32_32x32x16_bf16 v[32:47], v[128:131], v[72:75], v[32:47]
	v_exp_f32_e32 v126, v126
	v_exp_f32_e32 v127, v127
	ds_read_b64_tr_b16 v[72:73], v206 offset:39936
	ds_read_b64_tr_b16 v[74:75], v206 offset:40448
	s_waitcnt lgkmcnt(14)
	v_mfma_f32_32x32x16_bf16 v[16:31], v[140:143], v[76:79], v[16:31]
	v_exp_f32_e32 v96, v96
	v_exp_f32_e32 v97, v97
	s_lshl_b32 s31, s62, 13
	v_add_u32_e32 v160, s31, v239
	ds_read_b128 v[68:71], v160
	ds_read_b128 v[64:67], v160 offset:512
	s_waitcnt lgkmcnt(14)
	v_mfma_f32_32x32x16_bf16 v[0:15], v[140:143], v[80:83], v[0:15]
	v_exp_f32_e32 v98, v98
	v_exp_f32_e32 v99, v99
	ds_read_b128 v[180:183], v160 offset:2048
	ds_read_b128 v[176:179], v160 offset:2560
	s_waitcnt lgkmcnt(14)
	v_mfma_f32_32x32x16_bf16 v[16:31], v[136:139], v[84:87], v[16:31]
	v_exp_f32_e32 v100, v100
	v_exp_f32_e32 v101, v101
	ds_read_b128 v[172:175], v160 offset:4096
	ds_read_b128 v[168:171], v160 offset:4608
	s_waitcnt lgkmcnt(14)
	v_mfma_f32_32x32x16_bf16 v[0:15], v[136:139], v[88:91], v[0:15]
	v_exp_f32_e32 v102, v102
	v_exp_f32_e32 v103, v103
	ds_read_b128 v[164:167], v160 offset:6144
	ds_read_b128 v[160:163], v160 offset:6656
	s_waitcnt lgkmcnt(14)
	v_mfma_f32_32x32x16_bf16 v[16:31], v[132:135], v[92:95], v[16:31]
	v_exp_f32_e32 v104, v104
	v_exp_f32_e32 v105, v105
	s_waitcnt lgkmcnt(12)
	v_mfma_f32_32x32x16_bf16 v[0:15], v[132:135], v[196:199], v[0:15]
	v_exp_f32_e32 v106, v106
	v_exp_f32_e32 v107, v107
	s_waitcnt lgkmcnt(10)
	v_mfma_f32_32x32x16_bf16 v[16:31], v[128:131], v[200:203], v[16:31]
	v_exp_f32_e32 v108, v108
	v_exp_f32_e32 v109, v109
	s_waitcnt lgkmcnt(8)
	v_mfma_f32_32x32x16_bf16 v[0:15], v[128:131], v[72:75], v[0:15]
	v_exp_f32_e32 v110, v110
	v_exp_f32_e32 v111, v111
	s_waitcnt vmcnt(3) lgkmcnt(0)
	s_barrier
	s_add_i32 s33, s62, 1
	s_cmp_lg_u32 s62, 2
	s_cselect_b32 s61, s33, 0
	v_lshl_add_u32 v200, s3, 14, v241
	ds_read_b64_tr_b16 v[196:197], v200 offset:24576
	ds_read_b64_tr_b16 v[198:199], v200 offset:25088
	v_mfma_f32_32x32x16_bf16 v[80:95], v[68:71], v[156:159], 0
	v_add_f32_e32 v72, v112, v113
	v_add_f32_e32 v72, v114, v72
	v_add_f32_e32 v72, v115, v72
	v_add_f32_e32 v72, v116, v72
	v_add_f32_e32 v72, v117, v72
	v_cvt_pk_bf16_f32 v140, v112, v113
	v_cvt_pk_bf16_f32 v141, v114, v115
	ds_read_b64_tr_b16 v[112:113], v200 offset:28672
	ds_read_b64_tr_b16 v[114:115], v200 offset:29184
	v_add_f32_e32 v68, v118, v72
	v_add_f32_e32 v68, v119, v68
	v_add_f32_e32 v68, v120, v68
	v_add_f32_e32 v128, v121, v68
	v_mfma_f32_32x32x16_bf16 v[64:79], v[64:67], v[156:159], 0
	v_cvt_pk_bf16_f32 v142, v116, v117
	v_cvt_pk_bf16_f32 v143, v118, v119
	ds_read_b64_tr_b16 v[116:117], v200 offset:25600
	ds_read_b64_tr_b16 v[118:119], v200 offset:26112
	v_mfma_f32_32x32x16_bf16 v[80:95], v[180:183], v[152:155], v[80:95]
	v_add_f32_e32 v128, v122, v128
	v_add_f32_e32 v128, v123, v128
	v_add_f32_e32 v128, v124, v128
	v_add_f32_e32 v128, v125, v128
	v_cvt_pk_bf16_f32 v136, v120, v121
	v_cvt_pk_bf16_f32 v137, v122, v123
	ds_read_b64_tr_b16 v[120:121], v200 offset:29696
	ds_read_b64_tr_b16 v[122:123], v200 offset:30208
	v_mfma_f32_32x32x16_bf16 v[64:79], v[176:179], v[152:155], v[64:79]
	v_add_f32_e32 v128, v126, v128
	v_add_f32_e32 v128, v127, v128
	v_add_f32_e32 v128, v96, v128
	v_add_f32_e32 v128, v97, v128
	v_cvt_pk_bf16_f32 v138, v124, v125
	v_cvt_pk_bf16_f32 v139, v126, v127
	ds_read_b64_tr_b16 v[124:125], v200 offset:26624
	ds_read_b64_tr_b16 v[126:127], v200 offset:27136
	v_mfma_f32_32x32x16_bf16 v[80:95], v[172:175], v[148:151], v[80:95]
	v_add_f32_e32 v128, v98, v128
	v_add_f32_e32 v128, v99, v128
	v_add_f32_e32 v128, v100, v128
	v_add_f32_e32 v128, v101, v128
	v_cvt_pk_bf16_f32 v132, v96, v97
	v_cvt_pk_bf16_f32 v133, v98, v99
	ds_read_b64_tr_b16 v[96:97], v200 offset:30720
	ds_read_b64_tr_b16 v[98:99], v200 offset:31232
	v_mfma_f32_32x32x16_bf16 v[64:79], v[168:171], v[148:151], v[64:79]
	v_add_f32_e32 v128, v102, v128
	v_add_f32_e32 v128, v103, v128
	v_add_f32_e32 v128, v104, v128
	v_add_f32_e32 v128, v105, v128
	v_cvt_pk_bf16_f32 v134, v100, v101
	v_cvt_pk_bf16_f32 v135, v102, v103
	ds_read_b64_tr_b16 v[100:101], v200 offset:27648
	ds_read_b64_tr_b16 v[102:103], v200 offset:28160
	v_mfma_f32_32x32x16_bf16 v[80:95], v[164:167], v[144:147], v[80:95]
	v_add_f32_e32 v128, v106, v128
	v_add_f32_e32 v128, v107, v128
	v_add_f32_e32 v128, v108, v128
	v_add_f32_e32 v164, v109, v128
	v_cvt_pk_bf16_f32 v128, v104, v105
	v_cvt_pk_bf16_f32 v129, v106, v107
	ds_read_b64_tr_b16 v[104:105], v200 offset:31744
	ds_read_b64_tr_b16 v[106:107], v200 offset:32256
	v_mfma_f32_32x32x16_bf16 v[64:79], v[160:163], v[144:147], v[64:79]
	v_add_f32_e32 v130, v110, v164
	v_add_f32_e32 v130, v111, v130
	v_add_f32_e32 v160, 0, v130
	v_cvt_pk_bf16_f32 v130, v108, v109
	v_cvt_pk_bf16_f32 v131, v110, v111
	s_mov_b64 s[34:35], 0xb72aa00
	v_lshl_add_u64 v[108:109], v[186:187], 0, s[34:35]
	s_add_i32 s3, s31, s58
	s_mov_b32 s31, m0
	s_mov_b32 m0, s3
	s_nop 0
	global_load_lds_dwordx4 v[108:109], off
	s_mov_b32 m0, s31
	s_mov_b64 s[34:35], 0xb51ae00
	s_lshl_b32 s31, s61, 14
	v_lshl_add_u64 v[108:109], v[184:185], 0, s[34:35]
	s_add_i32 s3, s31, s59
	s_mov_b32 s33, m0
	s_mov_b32 m0, s3
	s_nop 0
	global_load_lds_dwordx4 v[108:109], off
	s_mov_b32 m0, s33
	s_mov_b64 s[34:35], 0xb51ae80
	v_lshl_add_u64 v[108:109], v[184:185], 0, s[34:35]
	s_addk_i32 s3, 0x2000
	s_mov_b32 s33, m0
	s_mov_b32 m0, s3
	s_nop 0
	global_load_lds_dwordx4 v[108:109], off
	s_mov_b32 m0, s33
	v_add_f32_e32 v204, v188, v160
	s_add_i32 s60, s60, 2
	s_waitcnt lgkmcnt(14)
	v_mfma_f32_32x32x16_bf16 v[48:63], v[140:143], v[196:199], v[48:63]
	v_exp_f32_e32 v80, v80
	v_exp_f32_e32 v81, v81
	ds_read_b64_tr_b16 v[108:109], v200 offset:32768
	ds_read_b64_tr_b16 v[110:111], v200 offset:33280
	s_waitcnt lgkmcnt(14)
	v_mfma_f32_32x32x16_bf16 v[32:47], v[140:143], v[112:115], v[32:47]
	v_exp_f32_e32 v82, v82
	v_exp_f32_e32 v83, v83
	ds_read_b64_tr_b16 v[112:113], v200 offset:36864
	ds_read_b64_tr_b16 v[114:115], v200 offset:37376
	s_waitcnt lgkmcnt(14)
	v_mfma_f32_32x32x16_bf16 v[48:63], v[136:139], v[116:119], v[48:63]
	v_exp_f32_e32 v84, v84
	v_exp_f32_e32 v85, v85
	ds_read_b64_tr_b16 v[116:117], v200 offset:33792
	ds_read_b64_tr_b16 v[118:119], v200 offset:34304
	s_waitcnt lgkmcnt(14)
	v_mfma_f32_32x32x16_bf16 v[32:47], v[136:139], v[120:123], v[32:47]
	v_exp_f32_e32 v86, v86
	v_exp_f32_e32 v87, v87
	ds_read_b64_tr_b16 v[120:121], v200 offset:37888
	ds_read_b64_tr_b16 v[122:123], v200 offset:38400
	s_waitcnt lgkmcnt(14)
	v_mfma_f32_32x32x16_bf16 v[48:63], v[132:135], v[124:127], v[48:63]
	v_exp_f32_e32 v88, v88
	v_exp_f32_e32 v89, v89
	ds_read_b64_tr_b16 v[124:125], v200 offset:34816
	ds_read_b64_tr_b16 v[126:127], v200 offset:35328
	s_waitcnt lgkmcnt(14)
	v_mfma_f32_32x32x16_bf16 v[32:47], v[132:135], v[96:99], v[32:47]
	v_exp_f32_e32 v90, v90
	v_exp_f32_e32 v91, v91
	ds_read_b64_tr_b16 v[96:97], v200 offset:38912
	ds_read_b64_tr_b16 v[98:99], v200 offset:39424
	s_waitcnt lgkmcnt(14)
	v_mfma_f32_32x32x16_bf16 v[48:63], v[128:131], v[100:103], v[48:63]
	v_exp_f32_e32 v92, v92
	v_exp_f32_e32 v93, v93
	ds_read_b64_tr_b16 v[100:101], v200 offset:35840
	ds_read_b64_tr_b16 v[102:103], v200 offset:36352
	s_waitcnt lgkmcnt(14)
	v_mfma_f32_32x32x16_bf16 v[32:47], v[128:131], v[104:107], v[32:47]
	v_exp_f32_e32 v94, v94
	v_exp_f32_e32 v95, v95
	ds_read_b64_tr_b16 v[104:105], v200 offset:39936
	ds_read_b64_tr_b16 v[106:107], v200 offset:40448
	s_waitcnt lgkmcnt(14)
	v_mfma_f32_32x32x16_bf16 v[16:31], v[140:143], v[108:111], v[16:31]
	v_exp_f32_e32 v64, v64
	v_exp_f32_e32 v65, v65
	v_lshl_add_u32 v160, s61, 13, v239
	ds_read_b128 v[188:191], v160
	ds_read_b128 v[180:183], v160 offset:512
	s_waitcnt lgkmcnt(14)
	v_mfma_f32_32x32x16_bf16 v[0:15], v[140:143], v[112:115], v[0:15]
	v_exp_f32_e32 v66, v66
	v_exp_f32_e32 v67, v67
	ds_read_b128 v[184:187], v160 offset:2048
	ds_read_b128 v[176:179], v160 offset:2560
	s_waitcnt lgkmcnt(14)
	v_mfma_f32_32x32x16_bf16 v[16:31], v[136:139], v[116:119], v[16:31]
	v_exp_f32_e32 v68, v68
	v_exp_f32_e32 v69, v69
	ds_read_b128 v[172:175], v160 offset:4096
	ds_read_b128 v[168:171], v160 offset:4608
	s_waitcnt lgkmcnt(14)
	v_mfma_f32_32x32x16_bf16 v[0:15], v[136:139], v[120:123], v[0:15]
	v_exp_f32_e32 v70, v70
	v_exp_f32_e32 v71, v71
	ds_read_b128 v[164:167], v160 offset:6144
	ds_read_b128 v[160:163], v160 offset:6656
	s_waitcnt lgkmcnt(14)
	v_mfma_f32_32x32x16_bf16 v[16:31], v[132:135], v[124:127], v[16:31]
	v_exp_f32_e32 v72, v72
	v_exp_f32_e32 v73, v73
	s_waitcnt lgkmcnt(12)
	v_mfma_f32_32x32x16_bf16 v[0:15], v[132:135], v[96:99], v[0:15]
	v_exp_f32_e32 v74, v74
	v_exp_f32_e32 v75, v75
	s_waitcnt lgkmcnt(10)
	v_mfma_f32_32x32x16_bf16 v[16:31], v[128:131], v[100:103], v[16:31]
	v_exp_f32_e32 v76, v76
	v_exp_f32_e32 v77, v77
	s_waitcnt lgkmcnt(8)
	v_mfma_f32_32x32x16_bf16 v[0:15], v[128:131], v[104:107], v[0:15]
	v_exp_f32_e32 v78, v78
	v_exp_f32_e32 v79, v79
	s_add_i32 s3, s61, 1
	s_waitcnt vmcnt(3) lgkmcnt(0)
	s_barrier
	s_cmp_lg_u32 s61, 2
	s_cselect_b32 s62, s3, 0
	s_add_i32 s33, s63, 2
	v_lshl_add_u64 v[192:193], v[192:193], 0, s[12:13]
	v_lshl_add_u64 v[194:195], v[194:195], 0, s[12:13]
	s_cmp_ge_u32 s60, s42
	v_lshl_add_u64 v[96:97], v[218:219], 0, s[12:13]
	s_mov_b32 s36, s30
	s_cbranch_scc0 .LBB0_442
	s_add_i32 s3, s60, 1
	s_cmp_ge_u32 s3, s41
	v_readlane_b32 s65, v252, 9
	s_cbranch_scc1 .LBB0_477
